# A steady loop tile 2: row-max chain consumes the earlier QK accumulator first, removing the 7-state s_nop bubble (bit-identical)
# speedup vs baseline: 1.0028x; 1.0028x over previous
.LBB0_386:
	s_add_i32 s2, s27, 0x2000
	s_cmpk_lg_i32 s27, 0x4000
	s_cselect_b32 s14, s2, 0
	v_add_u32_e32 v186, s3, v210
	ds_read_b64_tr_b16 v[150:151], v186 offset:24576
	ds_read_b64_tr_b16 v[152:153], v186 offset:25088
	s_waitcnt lgkmcnt(9)
	v_mfma_f32_32x32x16_bf16 v[66:81], v[62:65], v[130:133], v[34:49]
	v_add_f32_e32 v50, v98, v99
	v_add_f32_e32 v50, v100, v50
	v_add_f32_e32 v50, v101, v50
	v_add_f32_e32 v50, v102, v50
	v_add_f32_e32 v50, v103, v50
	v_cvt_pk_bf16_f32 v142, v98, v99
	v_cvt_pk_bf16_f32 v143, v100, v101
	ds_read_b64_tr_b16 v[146:147], v186 offset:28672
	ds_read_b64_tr_b16 v[148:149], v186 offset:29184
	v_add_f32_e32 v50, v104, v50
	v_add_f32_e32 v50, v105, v50
	v_add_f32_e32 v50, v106, v50
	v_add_f32_e32 v114, v107, v50
	s_waitcnt lgkmcnt(10)
	v_mfma_f32_32x32x16_bf16 v[50:65], v[174:177], v[130:133], v[34:49]
	v_cvt_pk_bf16_f32 v144, v102, v103
	v_cvt_pk_bf16_f32 v145, v104, v105
	ds_read_b64_tr_b16 v[98:99], v186 offset:25600
	ds_read_b64_tr_b16 v[100:101], v186 offset:26112
	s_waitcnt lgkmcnt(11)
	v_mfma_f32_32x32x16_bf16 v[66:81], v[178:181], v[122:125], v[66:81]
	v_add_f32_e32 v102, v108, v114
	v_add_f32_e32 v102, v109, v102
	v_add_f32_e32 v102, v110, v102
	v_add_f32_e32 v114, v111, v102
	v_cvt_pk_bf16_f32 v126, v106, v107
	v_cvt_pk_bf16_f32 v127, v108, v109
	ds_read_b64_tr_b16 v[102:103], v186 offset:29696
	ds_read_b64_tr_b16 v[104:105], v186 offset:30208
	s_waitcnt lgkmcnt(12)
	v_mfma_f32_32x32x16_bf16 v[50:65], v[170:173], v[122:125], v[50:65]
	v_add_f32_e32 v106, v112, v114
	v_add_f32_e32 v106, v113, v106
	v_add_f32_e32 v106, v82, v106
	v_add_f32_e32 v114, v83, v106
	v_cvt_pk_bf16_f32 v128, v110, v111
	v_cvt_pk_bf16_f32 v129, v112, v113
	ds_read_b64_tr_b16 v[106:107], v186 offset:26624
	ds_read_b64_tr_b16 v[108:109], v186 offset:27136
	s_waitcnt lgkmcnt(13)
	v_mfma_f32_32x32x16_bf16 v[66:81], v[166:169], v[138:141], v[66:81]
	v_add_f32_e32 v110, v84, v114
	v_add_f32_e32 v110, v85, v110
	v_add_f32_e32 v110, v86, v110
	v_add_f32_e32 v110, v87, v110
	v_cvt_pk_bf16_f32 v118, v82, v83
	v_cvt_pk_bf16_f32 v119, v84, v85
	ds_read_b64_tr_b16 v[82:83], v186 offset:30720
	ds_read_b64_tr_b16 v[84:85], v186 offset:31232
	s_waitcnt lgkmcnt(14)
	v_mfma_f32_32x32x16_bf16 v[50:65], v[162:165], v[138:141], v[50:65]
	v_add_f32_e32 v110, v88, v110
	v_add_f32_e32 v110, v89, v110
	v_add_f32_e32 v110, v90, v110
	v_add_f32_e32 v110, v91, v110
	v_cvt_pk_bf16_f32 v120, v86, v87
	v_cvt_pk_bf16_f32 v121, v88, v89
	ds_read_b64_tr_b16 v[86:87], v186 offset:27648
	ds_read_b64_tr_b16 v[88:89], v186 offset:28160
	s_waitcnt lgkmcnt(14)
	v_mfma_f32_32x32x16_bf16 v[66:81], v[158:161], v[134:137], v[66:81]
	v_add_f32_e32 v110, v92, v110
	v_add_f32_e32 v110, v93, v110
	v_add_f32_e32 v110, v94, v110
	v_add_f32_e32 v110, v95, v110
	v_cvt_pk_bf16_f32 v114, v90, v91
	v_cvt_pk_bf16_f32 v115, v92, v93
	ds_read_b64_tr_b16 v[90:91], v186 offset:31744
	ds_read_b64_tr_b16 v[92:93], v186 offset:32256
	v_mfma_f32_32x32x16_bf16 v[50:65], v[154:157], v[134:137], v[50:65]
	v_add_f32_e32 v110, v96, v110
	v_add_f32_e32 v110, v97, v110
	v_cvt_pk_bf16_f32 v116, v94, v95
	v_cvt_pk_bf16_f32 v117, v96, v97
	v_max_f32_e32 v94, v66, v67
	v_max3_f32 v95, v68, v69, v70
	v_max3_f32 v94, v94, v71, v72
	v_max3_f32 v95, v95, v73, v74
	v_max3_f32 v94, v94, v75, v76
	v_max3_f32 v95, v95, v77, v78
	v_max3_f32 v94, v94, v79, v80
	v_add_f32_e32 v212, v1, v110
	v_max3_f32 v95, v95, v81, v50
	v_max3_f32 v94, v94, v51, v52
	v_max3_f32 v95, v95, v53, v54
	v_max3_f32 v94, v94, v55, v56
	v_max3_f32 v95, v95, v57, v58
	v_max3_f32 v94, v94, v59, v60
	v_max3_f32 v95, v95, v61, v62
	v_max3_f32 v94, v94, v63, v64
	v_max3_f32 v1, v94, v65, v95
	s_add_i32 s2, s27, s22
	s_mov_b32 s3, m0
	s_mov_b32 m0, s2
	s_nop 0
	global_load_lds_dwordx4 v214, s[98:99]
	s_mov_b32 m0, s3
	s_add_i32 s2, s14, s23
	s_mov_b32 s3, m0
	s_mov_b32 m0, s2
	s_nop 0
	global_load_lds_dwordx4 v216, s[98:99]
	s_mov_b32 m0, s3
	v_cmp_lt_f32_e32 vcc, s19, v1
	s_cmp_lg_u64 vcc, 0
	s_cselect_b64 s[6:7], -1, 0
	s_cbranch_vccnz .LBB0_394
